# scanner: the operand wait of the next step fills the second DPP wait state (no s_nop per step)
# speedup vs baseline: 1.0013x; 1.0013x over previous
.LBB0_787:
	s_and_saveexec_b64 s[0:1], s[8:9]
	s_xor_b64 s[36:37], exec, s[0:1]
	s_cbranch_execz .LBB0_791
	s_and_saveexec_b64 s[44:45], s[26:27]
	s_cbranch_execz .LBB0_790
	s_and_b32 s0, s54, 1
	s_mul_i32 s1, s0, 0xc000
	s_lshl_b32 s4, s30, 2
	v_add_u32_e32 v10, s1, v97
	s_add_i32 s1, s1, s4
	v_lshl_add_u32 v11, v95, 2, s1
	v_lshl_add_u32 v12, s0, 14, v102
	v_pk_fma_f32 v[4:5], v[60:61], v[64:65], v[56:57] op_sel_hi:[0,1,1]
	v_pk_fma_f32 v[6:7], v[60:61], v[66:67], v[58:59] op_sel_hi:[0,1,1]
	v_pk_mul_f32 v[80:81], v[4:5], v[80:81]
	v_pk_fma_f32 v[80:81], v[6:7], v[82:83], v[80:81]
	v_add_f32_e32 v80, v80, v81
	v_pk_mul_f32 v[76:77], v[76:77], v[2:3] op_sel_hi:[1,0]
	v_pk_mul_f32 v[78:79], v[78:79], v[2:3] op_sel_hi:[1,0]
	v_add_f32_dpp v80, v80, v80 quad_perm:[1,0,3,2] row_mask:0xf bank_mask:0xf bound_ctrl:1
	v_pk_fma_f32 v[76:77], v[4:5], v[68:69], v[76:77]
	v_pk_fma_f32 v[78:79], v[6:7], v[70:71], v[78:79]
	v_add_f32_dpp v80, v80, v80 quad_perm:[2,3,0,1] row_mask:0xf bank_mask:0xf bound_ctrl:1
	v_pk_mul_f32 v[52:53], v[52:53], v[4:5]
	v_pk_fma_f32 v[52:53], v[6:7], v[54:55], v[52:53]
	ds_read_b128 v[36:39], v10 offset:512
	ds_read2st64_b32 v[0:1], v11 offset0:5 offset1:11
	ds_read_b128 v[40:43], v10 offset:768
	ds_read_b128 v[28:31], v10 offset:0
	ds_read_b128 v[44:47], v10 offset:1024
	ds_read_b128 v[32:35], v10 offset:256
	v_add_f32_dpp v80, v80, v80 row_half_mirror row_mask:0xf bank_mask:0xf bound_ctrl:1
	v_add_f32_e32 v9, v52, v53
	s_nop 0
	v_add_f32_dpp v80, v80, v80 row_mirror row_mask:0xf bank_mask:0xf bound_ctrl:1
	v_pk_fma_f32 v[4:5], v[80:81], v[84:85], v[76:77] op_sel_hi:[0,1,1]
	v_pk_fma_f32 v[6:7], v[80:81], v[86:87], v[78:79] op_sel_hi:[0,1,1]
	v_pk_mul_f32 v[116:117], v[4:5], v[116:117]
	v_pk_fma_f32 v[116:117], v[6:7], v[118:119], v[116:117]
	v_add_f32_e32 v116, v116, v117
	v_pk_mul_f32 v[112:113], v[112:113], v[2:3] op_sel:[0,1] op_sel_hi:[1,1]
	v_pk_mul_f32 v[114:115], v[114:115], v[2:3] op_sel:[0,1] op_sel_hi:[1,1]
	v_add_f32_dpp v116, v116, v116 quad_perm:[1,0,3,2] row_mask:0xf bank_mask:0xf bound_ctrl:1
	v_pk_fma_f32 v[112:113], v[4:5], v[104:105], v[112:113]
	v_pk_fma_f32 v[114:115], v[6:7], v[106:107], v[114:115]
	v_add_f32_dpp v116, v116, v116 quad_perm:[2,3,0,1] row_mask:0xf bank_mask:0xf bound_ctrl:1
	v_pk_mul_f32 v[72:73], v[72:73], v[4:5]
	v_pk_fma_f32 v[72:73], v[6:7], v[74:75], v[72:73]
	ds_read_b128 v[56:59], v10 offset:2048
	ds_read_b128 v[60:63], v10 offset:2304
	ds_read_b128 v[48:51], v10 offset:1536
	ds_read_b128 v[64:67], v10 offset:2560
	ds_read_b128 v[52:55], v10 offset:1792
	ds_write2st64_b32 v12, v8, v9 offset0:0 offset1:2
	v_add_f32_dpp v116, v116, v116 row_half_mirror row_mask:0xf bank_mask:0xf bound_ctrl:1
	v_add_f32_e32 v8, v72, v73
	s_waitcnt lgkmcnt(6)
	v_add_f32_dpp v116, v116, v116 row_mirror row_mask:0xf bank_mask:0xf bound_ctrl:1
	v_pk_fma_f32 v[4:5], v[116:117], v[120:121], v[112:113] op_sel_hi:[0,1,1]
	v_pk_fma_f32 v[6:7], v[116:117], v[122:123], v[114:115] op_sel_hi:[0,1,1]
	v_pk_mul_f32 v[40:41], v[4:5], v[40:41]
	v_pk_fma_f32 v[40:41], v[6:7], v[42:43], v[40:41]
	v_add_f32_e32 v40, v40, v41
	v_pk_mul_f32 v[36:37], v[36:37], v[0:1] op_sel_hi:[1,0]
	v_pk_mul_f32 v[38:39], v[38:39], v[0:1] op_sel_hi:[1,0]
	v_add_f32_dpp v40, v40, v40 quad_perm:[1,0,3,2] row_mask:0xf bank_mask:0xf bound_ctrl:1
	v_pk_fma_f32 v[36:37], v[4:5], v[28:29], v[36:37]
	v_pk_fma_f32 v[38:39], v[6:7], v[30:31], v[38:39]
	v_add_f32_dpp v40, v40, v40 quad_perm:[2,3,0,1] row_mask:0xf bank_mask:0xf bound_ctrl:1
	v_pk_mul_f32 v[108:109], v[108:109], v[4:5]
	v_pk_fma_f32 v[108:109], v[6:7], v[110:111], v[108:109]
	ds_read_b128 v[76:79], v10 offset:3584
	ds_read2st64_b32 v[2:3], v11 offset0:17 offset1:23
	ds_read_b128 v[80:83], v10 offset:3840
	ds_read_b128 v[68:71], v10 offset:3072
	ds_read_b128 v[84:87], v10 offset:4096
	ds_read_b128 v[72:75], v10 offset:3328
	v_add_f32_dpp v40, v40, v40 row_half_mirror row_mask:0xf bank_mask:0xf bound_ctrl:1
	v_add_f32_e32 v9, v108, v109
	s_waitcnt lgkmcnt(7)
	v_add_f32_dpp v40, v40, v40 row_mirror row_mask:0xf bank_mask:0xf bound_ctrl:1
	v_pk_fma_f32 v[4:5], v[40:41], v[44:45], v[36:37] op_sel_hi:[0,1,1]
	v_pk_fma_f32 v[6:7], v[40:41], v[46:47], v[38:39] op_sel_hi:[0,1,1]
	v_pk_mul_f32 v[60:61], v[4:5], v[60:61]
	v_pk_fma_f32 v[60:61], v[6:7], v[62:63], v[60:61]
	v_add_f32_e32 v60, v60, v61
	v_pk_mul_f32 v[56:57], v[56:57], v[0:1] op_sel:[0,1] op_sel_hi:[1,1]
	v_pk_mul_f32 v[58:59], v[58:59], v[0:1] op_sel:[0,1] op_sel_hi:[1,1]
	v_add_f32_dpp v60, v60, v60 quad_perm:[1,0,3,2] row_mask:0xf bank_mask:0xf bound_ctrl:1
	v_pk_fma_f32 v[56:57], v[4:5], v[48:49], v[56:57]
	v_pk_fma_f32 v[58:59], v[6:7], v[50:51], v[58:59]
	v_add_f32_dpp v60, v60, v60 quad_perm:[2,3,0,1] row_mask:0xf bank_mask:0xf bound_ctrl:1
	v_pk_mul_f32 v[32:33], v[32:33], v[4:5]
	v_pk_fma_f32 v[32:33], v[6:7], v[34:35], v[32:33]
	ds_read_b128 v[112:115], v10 offset:5120
	ds_read_b128 v[116:119], v10 offset:5376
	ds_read_b128 v[104:107], v10 offset:4608
	ds_read_b128 v[120:123], v10 offset:5632
	ds_read_b128 v[108:111], v10 offset:4864
	ds_write2st64_b32 v12, v8, v9 offset0:4 offset1:6
	v_add_f32_dpp v60, v60, v60 row_half_mirror row_mask:0xf bank_mask:0xf bound_ctrl:1
	v_add_f32_e32 v8, v32, v33
	s_waitcnt lgkmcnt(6)
	v_add_f32_dpp v60, v60, v60 row_mirror row_mask:0xf bank_mask:0xf bound_ctrl:1
	v_pk_fma_f32 v[4:5], v[60:61], v[64:65], v[56:57] op_sel_hi:[0,1,1]
	v_pk_fma_f32 v[6:7], v[60:61], v[66:67], v[58:59] op_sel_hi:[0,1,1]
	v_pk_mul_f32 v[80:81], v[4:5], v[80:81]
	v_pk_fma_f32 v[80:81], v[6:7], v[82:83], v[80:81]
	v_add_f32_e32 v80, v80, v81
	v_pk_mul_f32 v[76:77], v[76:77], v[2:3] op_sel_hi:[1,0]
	v_pk_mul_f32 v[78:79], v[78:79], v[2:3] op_sel_hi:[1,0]
	v_add_f32_dpp v80, v80, v80 quad_perm:[1,0,3,2] row_mask:0xf bank_mask:0xf bound_ctrl:1
	v_pk_fma_f32 v[76:77], v[4:5], v[68:69], v[76:77]
	v_pk_fma_f32 v[78:79], v[6:7], v[70:71], v[78:79]
	v_add_f32_dpp v80, v80, v80 quad_perm:[2,3,0,1] row_mask:0xf bank_mask:0xf bound_ctrl:1
	v_pk_mul_f32 v[52:53], v[52:53], v[4:5]
	v_pk_fma_f32 v[52:53], v[6:7], v[54:55], v[52:53]
	ds_read_b128 v[36:39], v10 offset:6656
	ds_read2st64_b32 v[0:1], v11 offset0:29 offset1:35
	ds_read_b128 v[40:43], v10 offset:6912
	ds_read_b128 v[28:31], v10 offset:6144
	ds_read_b128 v[44:47], v10 offset:7168
	ds_read_b128 v[32:35], v10 offset:6400
	v_add_f32_dpp v80, v80, v80 row_half_mirror row_mask:0xf bank_mask:0xf bound_ctrl:1
	v_add_f32_e32 v9, v52, v53
	s_waitcnt lgkmcnt(7)
	v_add_f32_dpp v80, v80, v80 row_mirror row_mask:0xf bank_mask:0xf bound_ctrl:1
	v_pk_fma_f32 v[4:5], v[80:81], v[84:85], v[76:77] op_sel_hi:[0,1,1]
	v_pk_fma_f32 v[6:7], v[80:81], v[86:87], v[78:79] op_sel_hi:[0,1,1]
	v_pk_mul_f32 v[116:117], v[4:5], v[116:117]
	v_pk_fma_f32 v[116:117], v[6:7], v[118:119], v[116:117]
	v_add_f32_e32 v116, v116, v117
	v_pk_mul_f32 v[112:113], v[112:113], v[2:3] op_sel:[0,1] op_sel_hi:[1,1]
	v_pk_mul_f32 v[114:115], v[114:115], v[2:3] op_sel:[0,1] op_sel_hi:[1,1]
	v_add_f32_dpp v116, v116, v116 quad_perm:[1,0,3,2] row_mask:0xf bank_mask:0xf bound_ctrl:1
	v_pk_fma_f32 v[112:113], v[4:5], v[104:105], v[112:113]
	v_pk_fma_f32 v[114:115], v[6:7], v[106:107], v[114:115]
	v_add_f32_dpp v116, v116, v116 quad_perm:[2,3,0,1] row_mask:0xf bank_mask:0xf bound_ctrl:1
	v_pk_mul_f32 v[72:73], v[72:73], v[4:5]
	v_pk_fma_f32 v[72:73], v[6:7], v[74:75], v[72:73]
	ds_read_b128 v[56:59], v10 offset:8192
	ds_read_b128 v[60:63], v10 offset:8448
	ds_read_b128 v[48:51], v10 offset:7680
	ds_read_b128 v[64:67], v10 offset:8704
	ds_read_b128 v[52:55], v10 offset:7936
	ds_write2st64_b32 v12, v8, v9 offset0:8 offset1:10
	v_add_f32_dpp v116, v116, v116 row_half_mirror row_mask:0xf bank_mask:0xf bound_ctrl:1
	v_add_f32_e32 v8, v72, v73
	s_waitcnt lgkmcnt(6)
	v_add_f32_dpp v116, v116, v116 row_mirror row_mask:0xf bank_mask:0xf bound_ctrl:1
	v_pk_fma_f32 v[4:5], v[116:117], v[120:121], v[112:113] op_sel_hi:[0,1,1]
	v_pk_fma_f32 v[6:7], v[116:117], v[122:123], v[114:115] op_sel_hi:[0,1,1]
	v_pk_mul_f32 v[40:41], v[4:5], v[40:41]
	v_pk_fma_f32 v[40:41], v[6:7], v[42:43], v[40:41]
	v_add_f32_e32 v40, v40, v41
	v_pk_mul_f32 v[36:37], v[36:37], v[0:1] op_sel_hi:[1,0]
	v_pk_mul_f32 v[38:39], v[38:39], v[0:1] op_sel_hi:[1,0]
	v_add_f32_dpp v40, v40, v40 quad_perm:[1,0,3,2] row_mask:0xf bank_mask:0xf bound_ctrl:1
	v_pk_fma_f32 v[36:37], v[4:5], v[28:29], v[36:37]
	v_pk_fma_f32 v[38:39], v[6:7], v[30:31], v[38:39]
	v_add_f32_dpp v40, v40, v40 quad_perm:[2,3,0,1] row_mask:0xf bank_mask:0xf bound_ctrl:1
	v_pk_mul_f32 v[108:109], v[108:109], v[4:5]
	v_pk_fma_f32 v[108:109], v[6:7], v[110:111], v[108:109]
	ds_read_b128 v[76:79], v10 offset:9728
	ds_read2st64_b32 v[2:3], v11 offset0:41 offset1:47
	ds_read_b128 v[80:83], v10 offset:9984
	ds_read_b128 v[68:71], v10 offset:9216
	ds_read_b128 v[84:87], v10 offset:10240
	ds_read_b128 v[72:75], v10 offset:9472
	v_add_f32_dpp v40, v40, v40 row_half_mirror row_mask:0xf bank_mask:0xf bound_ctrl:1
	v_add_f32_e32 v9, v108, v109
	s_waitcnt lgkmcnt(7)
	v_add_f32_dpp v40, v40, v40 row_mirror row_mask:0xf bank_mask:0xf bound_ctrl:1
	v_pk_fma_f32 v[4:5], v[40:41], v[44:45], v[36:37] op_sel_hi:[0,1,1]
	v_pk_fma_f32 v[6:7], v[40:41], v[46:47], v[38:39] op_sel_hi:[0,1,1]
	v_pk_mul_f32 v[60:61], v[4:5], v[60:61]
	v_pk_fma_f32 v[60:61], v[6:7], v[62:63], v[60:61]
	v_add_f32_e32 v60, v60, v61
	v_pk_mul_f32 v[56:57], v[56:57], v[0:1] op_sel:[0,1] op_sel_hi:[1,1]
	v_pk_mul_f32 v[58:59], v[58:59], v[0:1] op_sel:[0,1] op_sel_hi:[1,1]
	v_add_f32_dpp v60, v60, v60 quad_perm:[1,0,3,2] row_mask:0xf bank_mask:0xf bound_ctrl:1
	v_pk_fma_f32 v[56:57], v[4:5], v[48:49], v[56:57]
	v_pk_fma_f32 v[58:59], v[6:7], v[50:51], v[58:59]
	v_add_f32_dpp v60, v60, v60 quad_perm:[2,3,0,1] row_mask:0xf bank_mask:0xf bound_ctrl:1
	v_pk_mul_f32 v[32:33], v[32:33], v[4:5]
	v_pk_fma_f32 v[32:33], v[6:7], v[34:35], v[32:33]
	ds_read_b128 v[112:115], v10 offset:11264
	ds_read_b128 v[116:119], v10 offset:11520
	ds_read_b128 v[104:107], v10 offset:10752
	ds_read_b128 v[120:123], v10 offset:11776
	ds_read_b128 v[108:111], v10 offset:11008
	ds_write2st64_b32 v12, v8, v9 offset0:12 offset1:14
	v_add_f32_dpp v60, v60, v60 row_half_mirror row_mask:0xf bank_mask:0xf bound_ctrl:1
	v_add_f32_e32 v8, v32, v33
	s_waitcnt lgkmcnt(6)
	v_add_f32_dpp v60, v60, v60 row_mirror row_mask:0xf bank_mask:0xf bound_ctrl:1
	v_pk_fma_f32 v[4:5], v[60:61], v[64:65], v[56:57] op_sel_hi:[0,1,1]
	v_pk_fma_f32 v[6:7], v[60:61], v[66:67], v[58:59] op_sel_hi:[0,1,1]
	v_pk_mul_f32 v[80:81], v[4:5], v[80:81]
	v_pk_fma_f32 v[80:81], v[6:7], v[82:83], v[80:81]
	v_add_f32_e32 v80, v80, v81
	v_pk_mul_f32 v[76:77], v[76:77], v[2:3] op_sel_hi:[1,0]
	v_pk_mul_f32 v[78:79], v[78:79], v[2:3] op_sel_hi:[1,0]
	v_add_f32_dpp v80, v80, v80 quad_perm:[1,0,3,2] row_mask:0xf bank_mask:0xf bound_ctrl:1
	v_pk_fma_f32 v[76:77], v[4:5], v[68:69], v[76:77]
	v_pk_fma_f32 v[78:79], v[6:7], v[70:71], v[78:79]
	v_add_f32_dpp v80, v80, v80 quad_perm:[2,3,0,1] row_mask:0xf bank_mask:0xf bound_ctrl:1
	v_pk_mul_f32 v[52:53], v[52:53], v[4:5]
	v_pk_fma_f32 v[52:53], v[6:7], v[54:55], v[52:53]
	ds_read_b128 v[36:39], v10 offset:12800
	ds_read2st64_b32 v[0:1], v11 offset0:53 offset1:59
	ds_read_b128 v[40:43], v10 offset:13056
	ds_read_b128 v[28:31], v10 offset:12288
	ds_read_b128 v[44:47], v10 offset:13312
	ds_read_b128 v[32:35], v10 offset:12544
	v_add_f32_dpp v80, v80, v80 row_half_mirror row_mask:0xf bank_mask:0xf bound_ctrl:1
	v_add_f32_e32 v9, v52, v53
	s_waitcnt lgkmcnt(7)
	v_add_f32_dpp v80, v80, v80 row_mirror row_mask:0xf bank_mask:0xf bound_ctrl:1
	v_pk_fma_f32 v[4:5], v[80:81], v[84:85], v[76:77] op_sel_hi:[0,1,1]
	v_pk_fma_f32 v[6:7], v[80:81], v[86:87], v[78:79] op_sel_hi:[0,1,1]
	v_pk_mul_f32 v[116:117], v[4:5], v[116:117]
	v_pk_fma_f32 v[116:117], v[6:7], v[118:119], v[116:117]
	v_add_f32_e32 v116, v116, v117
	v_pk_mul_f32 v[112:113], v[112:113], v[2:3] op_sel:[0,1] op_sel_hi:[1,1]
	v_pk_mul_f32 v[114:115], v[114:115], v[2:3] op_sel:[0,1] op_sel_hi:[1,1]
	v_add_f32_dpp v116, v116, v116 quad_perm:[1,0,3,2] row_mask:0xf bank_mask:0xf bound_ctrl:1
	v_pk_fma_f32 v[112:113], v[4:5], v[104:105], v[112:113]
	v_pk_fma_f32 v[114:115], v[6:7], v[106:107], v[114:115]
	v_add_f32_dpp v116, v116, v116 quad_perm:[2,3,0,1] row_mask:0xf bank_mask:0xf bound_ctrl:1
	v_pk_mul_f32 v[72:73], v[72:73], v[4:5]
	v_pk_fma_f32 v[72:73], v[6:7], v[74:75], v[72:73]
	ds_read_b128 v[56:59], v10 offset:14336
	ds_read_b128 v[60:63], v10 offset:14592
	ds_read_b128 v[48:51], v10 offset:13824
	ds_read_b128 v[64:67], v10 offset:14848
	ds_read_b128 v[52:55], v10 offset:14080
	ds_write2st64_b32 v12, v8, v9 offset0:16 offset1:18
	v_add_f32_dpp v116, v116, v116 row_half_mirror row_mask:0xf bank_mask:0xf bound_ctrl:1
	v_add_f32_e32 v8, v72, v73
	s_waitcnt lgkmcnt(6)
	v_add_f32_dpp v116, v116, v116 row_mirror row_mask:0xf bank_mask:0xf bound_ctrl:1
	v_pk_fma_f32 v[4:5], v[116:117], v[120:121], v[112:113] op_sel_hi:[0,1,1]
	v_pk_fma_f32 v[6:7], v[116:117], v[122:123], v[114:115] op_sel_hi:[0,1,1]
	v_pk_mul_f32 v[40:41], v[4:5], v[40:41]
	v_pk_fma_f32 v[40:41], v[6:7], v[42:43], v[40:41]
	v_add_f32_e32 v40, v40, v41
	v_pk_mul_f32 v[36:37], v[36:37], v[0:1] op_sel_hi:[1,0]
	v_pk_mul_f32 v[38:39], v[38:39], v[0:1] op_sel_hi:[1,0]
	v_add_f32_dpp v40, v40, v40 quad_perm:[1,0,3,2] row_mask:0xf bank_mask:0xf bound_ctrl:1
	v_pk_fma_f32 v[36:37], v[4:5], v[28:29], v[36:37]
	v_pk_fma_f32 v[38:39], v[6:7], v[30:31], v[38:39]
	v_add_f32_dpp v40, v40, v40 quad_perm:[2,3,0,1] row_mask:0xf bank_mask:0xf bound_ctrl:1
	v_pk_mul_f32 v[108:109], v[108:109], v[4:5]
	v_pk_fma_f32 v[108:109], v[6:7], v[110:111], v[108:109]
	ds_read_b128 v[76:79], v10 offset:15872
	ds_read2st64_b32 v[2:3], v11 offset0:65 offset1:71
	ds_read_b128 v[80:83], v10 offset:16128
	ds_read_b128 v[68:71], v10 offset:15360
	ds_read_b128 v[84:87], v10 offset:16384
	ds_read_b128 v[72:75], v10 offset:15616
	v_add_f32_dpp v40, v40, v40 row_half_mirror row_mask:0xf bank_mask:0xf bound_ctrl:1
	v_add_f32_e32 v9, v108, v109
	s_waitcnt lgkmcnt(7)
	v_add_f32_dpp v40, v40, v40 row_mirror row_mask:0xf bank_mask:0xf bound_ctrl:1
	v_pk_fma_f32 v[4:5], v[40:41], v[44:45], v[36:37] op_sel_hi:[0,1,1]
	v_pk_fma_f32 v[6:7], v[40:41], v[46:47], v[38:39] op_sel_hi:[0,1,1]
	v_pk_mul_f32 v[60:61], v[4:5], v[60:61]
	v_pk_fma_f32 v[60:61], v[6:7], v[62:63], v[60:61]
	v_add_f32_e32 v60, v60, v61
	v_pk_mul_f32 v[56:57], v[56:57], v[0:1] op_sel:[0,1] op_sel_hi:[1,1]
	v_pk_mul_f32 v[58:59], v[58:59], v[0:1] op_sel:[0,1] op_sel_hi:[1,1]
	v_add_f32_dpp v60, v60, v60 quad_perm:[1,0,3,2] row_mask:0xf bank_mask:0xf bound_ctrl:1
	v_pk_fma_f32 v[56:57], v[4:5], v[48:49], v[56:57]
	v_pk_fma_f32 v[58:59], v[6:7], v[50:51], v[58:59]
	v_add_f32_dpp v60, v60, v60 quad_perm:[2,3,0,1] row_mask:0xf bank_mask:0xf bound_ctrl:1
	v_pk_mul_f32 v[32:33], v[32:33], v[4:5]
	v_pk_fma_f32 v[32:33], v[6:7], v[34:35], v[32:33]
	ds_read_b128 v[112:115], v10 offset:17408
	ds_read_b128 v[116:119], v10 offset:17664
	ds_read_b128 v[104:107], v10 offset:16896
	ds_read_b128 v[120:123], v10 offset:17920
	ds_read_b128 v[108:111], v10 offset:17152
	ds_write2st64_b32 v12, v8, v9 offset0:20 offset1:22
	v_add_f32_dpp v60, v60, v60 row_half_mirror row_mask:0xf bank_mask:0xf bound_ctrl:1
	v_add_f32_e32 v8, v32, v33
	s_waitcnt lgkmcnt(6)
	v_add_f32_dpp v60, v60, v60 row_mirror row_mask:0xf bank_mask:0xf bound_ctrl:1
	v_pk_fma_f32 v[4:5], v[60:61], v[64:65], v[56:57] op_sel_hi:[0,1,1]
	v_pk_fma_f32 v[6:7], v[60:61], v[66:67], v[58:59] op_sel_hi:[0,1,1]
	v_pk_mul_f32 v[80:81], v[4:5], v[80:81]
	v_pk_fma_f32 v[80:81], v[6:7], v[82:83], v[80:81]
	v_add_f32_e32 v80, v80, v81
	v_pk_mul_f32 v[76:77], v[76:77], v[2:3] op_sel_hi:[1,0]
	v_pk_mul_f32 v[78:79], v[78:79], v[2:3] op_sel_hi:[1,0]
	v_add_f32_dpp v80, v80, v80 quad_perm:[1,0,3,2] row_mask:0xf bank_mask:0xf bound_ctrl:1
	v_pk_fma_f32 v[76:77], v[4:5], v[68:69], v[76:77]
	v_pk_fma_f32 v[78:79], v[6:7], v[70:71], v[78:79]
	v_add_f32_dpp v80, v80, v80 quad_perm:[2,3,0,1] row_mask:0xf bank_mask:0xf bound_ctrl:1
	v_pk_mul_f32 v[52:53], v[52:53], v[4:5]
	v_pk_fma_f32 v[52:53], v[6:7], v[54:55], v[52:53]
	ds_read_b128 v[36:39], v10 offset:18944
	ds_read2st64_b32 v[0:1], v11 offset0:77 offset1:83
	ds_read_b128 v[40:43], v10 offset:19200
	ds_read_b128 v[28:31], v10 offset:18432
	ds_read_b128 v[44:47], v10 offset:19456
	ds_read_b128 v[32:35], v10 offset:18688
	v_add_f32_dpp v80, v80, v80 row_half_mirror row_mask:0xf bank_mask:0xf bound_ctrl:1
	v_add_f32_e32 v9, v52, v53
	s_waitcnt lgkmcnt(7)
	v_add_f32_dpp v80, v80, v80 row_mirror row_mask:0xf bank_mask:0xf bound_ctrl:1
	v_pk_fma_f32 v[4:5], v[80:81], v[84:85], v[76:77] op_sel_hi:[0,1,1]
	v_pk_fma_f32 v[6:7], v[80:81], v[86:87], v[78:79] op_sel_hi:[0,1,1]
	v_pk_mul_f32 v[116:117], v[4:5], v[116:117]
	v_pk_fma_f32 v[116:117], v[6:7], v[118:119], v[116:117]
	v_add_f32_e32 v116, v116, v117
	v_pk_mul_f32 v[112:113], v[112:113], v[2:3] op_sel:[0,1] op_sel_hi:[1,1]
	v_pk_mul_f32 v[114:115], v[114:115], v[2:3] op_sel:[0,1] op_sel_hi:[1,1]
	v_add_f32_dpp v116, v116, v116 quad_perm:[1,0,3,2] row_mask:0xf bank_mask:0xf bound_ctrl:1
	v_pk_fma_f32 v[112:113], v[4:5], v[104:105], v[112:113]
	v_pk_fma_f32 v[114:115], v[6:7], v[106:107], v[114:115]
	v_add_f32_dpp v116, v116, v116 quad_perm:[2,3,0,1] row_mask:0xf bank_mask:0xf bound_ctrl:1
	v_pk_mul_f32 v[72:73], v[72:73], v[4:5]
	v_pk_fma_f32 v[72:73], v[6:7], v[74:75], v[72:73]
	ds_read_b128 v[56:59], v10 offset:20480
	ds_read_b128 v[60:63], v10 offset:20736
	ds_read_b128 v[48:51], v10 offset:19968
	ds_read_b128 v[64:67], v10 offset:20992
	ds_read_b128 v[52:55], v10 offset:20224
	ds_write2st64_b32 v12, v8, v9 offset0:24 offset1:26
	v_add_f32_dpp v116, v116, v116 row_half_mirror row_mask:0xf bank_mask:0xf bound_ctrl:1
	v_add_f32_e32 v8, v72, v73
	s_waitcnt lgkmcnt(6)
	v_add_f32_dpp v116, v116, v116 row_mirror row_mask:0xf bank_mask:0xf bound_ctrl:1
	v_pk_fma_f32 v[4:5], v[116:117], v[120:121], v[112:113] op_sel_hi:[0,1,1]
	v_pk_fma_f32 v[6:7], v[116:117], v[122:123], v[114:115] op_sel_hi:[0,1,1]
	v_pk_mul_f32 v[40:41], v[4:5], v[40:41]
	v_pk_fma_f32 v[40:41], v[6:7], v[42:43], v[40:41]
	v_add_f32_e32 v40, v40, v41
	v_pk_mul_f32 v[36:37], v[36:37], v[0:1] op_sel_hi:[1,0]
	v_pk_mul_f32 v[38:39], v[38:39], v[0:1] op_sel_hi:[1,0]
	v_add_f32_dpp v40, v40, v40 quad_perm:[1,0,3,2] row_mask:0xf bank_mask:0xf bound_ctrl:1
	v_pk_fma_f32 v[36:37], v[4:5], v[28:29], v[36:37]
	v_pk_fma_f32 v[38:39], v[6:7], v[30:31], v[38:39]
	v_add_f32_dpp v40, v40, v40 quad_perm:[2,3,0,1] row_mask:0xf bank_mask:0xf bound_ctrl:1
	v_pk_mul_f32 v[108:109], v[108:109], v[4:5]
	v_pk_fma_f32 v[108:109], v[6:7], v[110:111], v[108:109]
	ds_read_b128 v[76:79], v10 offset:22016
	ds_read2st64_b32 v[2:3], v11 offset0:89 offset1:95
	ds_read_b128 v[80:83], v10 offset:22272
	ds_read_b128 v[68:71], v10 offset:21504
	ds_read_b128 v[84:87], v10 offset:22528
	ds_read_b128 v[72:75], v10 offset:21760
	v_add_f32_dpp v40, v40, v40 row_half_mirror row_mask:0xf bank_mask:0xf bound_ctrl:1
	v_add_f32_e32 v9, v108, v109
	s_waitcnt lgkmcnt(7)
	v_add_f32_dpp v40, v40, v40 row_mirror row_mask:0xf bank_mask:0xf bound_ctrl:1
	v_pk_fma_f32 v[4:5], v[40:41], v[44:45], v[36:37] op_sel_hi:[0,1,1]
	v_pk_fma_f32 v[6:7], v[40:41], v[46:47], v[38:39] op_sel_hi:[0,1,1]
	v_pk_mul_f32 v[60:61], v[4:5], v[60:61]
	v_pk_fma_f32 v[60:61], v[6:7], v[62:63], v[60:61]
	v_add_f32_e32 v60, v60, v61
	v_pk_mul_f32 v[56:57], v[56:57], v[0:1] op_sel:[0,1] op_sel_hi:[1,1]
	v_pk_mul_f32 v[58:59], v[58:59], v[0:1] op_sel:[0,1] op_sel_hi:[1,1]
	v_add_f32_dpp v60, v60, v60 quad_perm:[1,0,3,2] row_mask:0xf bank_mask:0xf bound_ctrl:1
	v_pk_fma_f32 v[56:57], v[4:5], v[48:49], v[56:57]
	v_pk_fma_f32 v[58:59], v[6:7], v[50:51], v[58:59]
	v_add_f32_dpp v60, v60, v60 quad_perm:[2,3,0,1] row_mask:0xf bank_mask:0xf bound_ctrl:1
	v_pk_mul_f32 v[32:33], v[32:33], v[4:5]
	v_pk_fma_f32 v[32:33], v[6:7], v[34:35], v[32:33]
	ds_read_b128 v[112:115], v10 offset:23552
	ds_read_b128 v[116:119], v10 offset:23808
	ds_read_b128 v[104:107], v10 offset:23040
	ds_read_b128 v[120:123], v10 offset:24064
	ds_read_b128 v[108:111], v10 offset:23296
	ds_write2st64_b32 v12, v8, v9 offset0:28 offset1:30
	v_add_f32_dpp v60, v60, v60 row_half_mirror row_mask:0xf bank_mask:0xf bound_ctrl:1
	v_add_f32_e32 v8, v32, v33
	s_waitcnt lgkmcnt(6)
	v_add_f32_dpp v60, v60, v60 row_mirror row_mask:0xf bank_mask:0xf bound_ctrl:1
	v_pk_fma_f32 v[4:5], v[60:61], v[64:65], v[56:57] op_sel_hi:[0,1,1]
	v_pk_fma_f32 v[6:7], v[60:61], v[66:67], v[58:59] op_sel_hi:[0,1,1]
	v_pk_mul_f32 v[80:81], v[4:5], v[80:81]
	v_pk_fma_f32 v[80:81], v[6:7], v[82:83], v[80:81]
	v_add_f32_e32 v80, v80, v81
	v_pk_mul_f32 v[76:77], v[76:77], v[2:3] op_sel_hi:[1,0]
	v_pk_mul_f32 v[78:79], v[78:79], v[2:3] op_sel_hi:[1,0]
	v_add_f32_dpp v80, v80, v80 quad_perm:[1,0,3,2] row_mask:0xf bank_mask:0xf bound_ctrl:1
	v_pk_fma_f32 v[76:77], v[4:5], v[68:69], v[76:77]
	v_pk_fma_f32 v[78:79], v[6:7], v[70:71], v[78:79]
	v_add_f32_dpp v80, v80, v80 quad_perm:[2,3,0,1] row_mask:0xf bank_mask:0xf bound_ctrl:1
	v_pk_mul_f32 v[52:53], v[52:53], v[4:5]
	v_pk_fma_f32 v[52:53], v[6:7], v[54:55], v[52:53]
	ds_read_b128 v[36:39], v10 offset:25088
	ds_read2st64_b32 v[0:1], v11 offset0:101 offset1:107
	ds_read_b128 v[40:43], v10 offset:25344
	ds_read_b128 v[28:31], v10 offset:24576
	ds_read_b128 v[44:47], v10 offset:25600
	ds_read_b128 v[32:35], v10 offset:24832
	v_add_f32_dpp v80, v80, v80 row_half_mirror row_mask:0xf bank_mask:0xf bound_ctrl:1
	v_add_f32_e32 v9, v52, v53
	s_waitcnt lgkmcnt(7)
	v_add_f32_dpp v80, v80, v80 row_mirror row_mask:0xf bank_mask:0xf bound_ctrl:1
	v_pk_fma_f32 v[4:5], v[80:81], v[84:85], v[76:77] op_sel_hi:[0,1,1]
	v_pk_fma_f32 v[6:7], v[80:81], v[86:87], v[78:79] op_sel_hi:[0,1,1]
	v_pk_mul_f32 v[116:117], v[4:5], v[116:117]
	v_pk_fma_f32 v[116:117], v[6:7], v[118:119], v[116:117]
	v_add_f32_e32 v116, v116, v117
	v_pk_mul_f32 v[112:113], v[112:113], v[2:3] op_sel:[0,1] op_sel_hi:[1,1]
	v_pk_mul_f32 v[114:115], v[114:115], v[2:3] op_sel:[0,1] op_sel_hi:[1,1]
	v_add_f32_dpp v116, v116, v116 quad_perm:[1,0,3,2] row_mask:0xf bank_mask:0xf bound_ctrl:1
	v_pk_fma_f32 v[112:113], v[4:5], v[104:105], v[112:113]
	v_pk_fma_f32 v[114:115], v[6:7], v[106:107], v[114:115]
	v_add_f32_dpp v116, v116, v116 quad_perm:[2,3,0,1] row_mask:0xf bank_mask:0xf bound_ctrl:1
	v_pk_mul_f32 v[72:73], v[72:73], v[4:5]
	v_pk_fma_f32 v[72:73], v[6:7], v[74:75], v[72:73]
	ds_read_b128 v[56:59], v10 offset:26624
	ds_read_b128 v[60:63], v10 offset:26880
	ds_read_b128 v[48:51], v10 offset:26112
	ds_read_b128 v[64:67], v10 offset:27136
	ds_read_b128 v[52:55], v10 offset:26368
	ds_write2st64_b32 v12, v8, v9 offset0:32 offset1:34
	v_add_f32_dpp v116, v116, v116 row_half_mirror row_mask:0xf bank_mask:0xf bound_ctrl:1
	v_add_f32_e32 v8, v72, v73
	s_waitcnt lgkmcnt(6)
	v_add_f32_dpp v116, v116, v116 row_mirror row_mask:0xf bank_mask:0xf bound_ctrl:1
	v_pk_fma_f32 v[4:5], v[116:117], v[120:121], v[112:113] op_sel_hi:[0,1,1]
	v_pk_fma_f32 v[6:7], v[116:117], v[122:123], v[114:115] op_sel_hi:[0,1,1]
	v_pk_mul_f32 v[40:41], v[4:5], v[40:41]
	v_pk_fma_f32 v[40:41], v[6:7], v[42:43], v[40:41]
	v_add_f32_e32 v40, v40, v41
	v_pk_mul_f32 v[36:37], v[36:37], v[0:1] op_sel_hi:[1,0]
	v_pk_mul_f32 v[38:39], v[38:39], v[0:1] op_sel_hi:[1,0]
	v_add_f32_dpp v40, v40, v40 quad_perm:[1,0,3,2] row_mask:0xf bank_mask:0xf bound_ctrl:1
	v_pk_fma_f32 v[36:37], v[4:5], v[28:29], v[36:37]
	v_pk_fma_f32 v[38:39], v[6:7], v[30:31], v[38:39]
	v_add_f32_dpp v40, v40, v40 quad_perm:[2,3,0,1] row_mask:0xf bank_mask:0xf bound_ctrl:1
	v_pk_mul_f32 v[108:109], v[108:109], v[4:5]
	v_pk_fma_f32 v[108:109], v[6:7], v[110:111], v[108:109]
	ds_read_b128 v[76:79], v10 offset:28160
	ds_read2st64_b32 v[2:3], v11 offset0:113 offset1:119
	ds_read_b128 v[80:83], v10 offset:28416
	ds_read_b128 v[68:71], v10 offset:27648
	ds_read_b128 v[84:87], v10 offset:28672
	ds_read_b128 v[72:75], v10 offset:27904
	v_add_f32_dpp v40, v40, v40 row_half_mirror row_mask:0xf bank_mask:0xf bound_ctrl:1
	v_add_f32_e32 v9, v108, v109
	s_waitcnt lgkmcnt(7)
	v_add_f32_dpp v40, v40, v40 row_mirror row_mask:0xf bank_mask:0xf bound_ctrl:1
	v_pk_fma_f32 v[4:5], v[40:41], v[44:45], v[36:37] op_sel_hi:[0,1,1]
	v_pk_fma_f32 v[6:7], v[40:41], v[46:47], v[38:39] op_sel_hi:[0,1,1]
	v_pk_mul_f32 v[60:61], v[4:5], v[60:61]
	v_pk_fma_f32 v[60:61], v[6:7], v[62:63], v[60:61]
	v_add_f32_e32 v60, v60, v61
	v_pk_mul_f32 v[56:57], v[56:57], v[0:1] op_sel:[0,1] op_sel_hi:[1,1]
	v_pk_mul_f32 v[58:59], v[58:59], v[0:1] op_sel:[0,1] op_sel_hi:[1,1]
	v_add_f32_dpp v60, v60, v60 quad_perm:[1,0,3,2] row_mask:0xf bank_mask:0xf bound_ctrl:1
	v_pk_fma_f32 v[56:57], v[4:5], v[48:49], v[56:57]
	v_pk_fma_f32 v[58:59], v[6:7], v[50:51], v[58:59]
	v_add_f32_dpp v60, v60, v60 quad_perm:[2,3,0,1] row_mask:0xf bank_mask:0xf bound_ctrl:1
	v_pk_mul_f32 v[32:33], v[32:33], v[4:5]
	v_pk_fma_f32 v[32:33], v[6:7], v[34:35], v[32:33]
	ds_read_b128 v[112:115], v10 offset:29696
	ds_read_b128 v[116:119], v10 offset:29952
	ds_read_b128 v[104:107], v10 offset:29184
	ds_read_b128 v[120:123], v10 offset:30208
	ds_read_b128 v[108:111], v10 offset:29440
	ds_write2st64_b32 v12, v8, v9 offset0:36 offset1:38
	v_add_f32_dpp v60, v60, v60 row_half_mirror row_mask:0xf bank_mask:0xf bound_ctrl:1
	v_add_f32_e32 v8, v32, v33
	s_waitcnt lgkmcnt(6)
	v_add_f32_dpp v60, v60, v60 row_mirror row_mask:0xf bank_mask:0xf bound_ctrl:1
	v_pk_fma_f32 v[4:5], v[60:61], v[64:65], v[56:57] op_sel_hi:[0,1,1]
	v_pk_fma_f32 v[6:7], v[60:61], v[66:67], v[58:59] op_sel_hi:[0,1,1]
	v_pk_mul_f32 v[80:81], v[4:5], v[80:81]
	v_pk_fma_f32 v[80:81], v[6:7], v[82:83], v[80:81]
	v_add_f32_e32 v80, v80, v81
	v_pk_mul_f32 v[76:77], v[76:77], v[2:3] op_sel_hi:[1,0]
	v_pk_mul_f32 v[78:79], v[78:79], v[2:3] op_sel_hi:[1,0]
	v_add_f32_dpp v80, v80, v80 quad_perm:[1,0,3,2] row_mask:0xf bank_mask:0xf bound_ctrl:1
	v_pk_fma_f32 v[76:77], v[4:5], v[68:69], v[76:77]
	v_pk_fma_f32 v[78:79], v[6:7], v[70:71], v[78:79]
	v_add_f32_dpp v80, v80, v80 quad_perm:[2,3,0,1] row_mask:0xf bank_mask:0xf bound_ctrl:1
	v_pk_mul_f32 v[52:53], v[52:53], v[4:5]
	v_pk_fma_f32 v[52:53], v[6:7], v[54:55], v[52:53]
	ds_read_b128 v[36:39], v10 offset:31232
	ds_read2st64_b32 v[0:1], v11 offset0:125 offset1:131
	ds_read_b128 v[40:43], v10 offset:31488
	ds_read_b128 v[28:31], v10 offset:30720
	ds_read_b128 v[44:47], v10 offset:31744
	ds_read_b128 v[32:35], v10 offset:30976
	v_add_f32_dpp v80, v80, v80 row_half_mirror row_mask:0xf bank_mask:0xf bound_ctrl:1
	v_add_f32_e32 v9, v52, v53
	s_waitcnt lgkmcnt(7)
	v_add_f32_dpp v80, v80, v80 row_mirror row_mask:0xf bank_mask:0xf bound_ctrl:1
	v_pk_fma_f32 v[4:5], v[80:81], v[84:85], v[76:77] op_sel_hi:[0,1,1]
	v_pk_fma_f32 v[6:7], v[80:81], v[86:87], v[78:79] op_sel_hi:[0,1,1]
	v_pk_mul_f32 v[116:117], v[4:5], v[116:117]
	v_pk_fma_f32 v[116:117], v[6:7], v[118:119], v[116:117]
	v_add_f32_e32 v116, v116, v117
	v_pk_mul_f32 v[112:113], v[112:113], v[2:3] op_sel:[0,1] op_sel_hi:[1,1]
	v_pk_mul_f32 v[114:115], v[114:115], v[2:3] op_sel:[0,1] op_sel_hi:[1,1]
	v_add_f32_dpp v116, v116, v116 quad_perm:[1,0,3,2] row_mask:0xf bank_mask:0xf bound_ctrl:1
	v_pk_fma_f32 v[112:113], v[4:5], v[104:105], v[112:113]
	v_pk_fma_f32 v[114:115], v[6:7], v[106:107], v[114:115]
	v_add_f32_dpp v116, v116, v116 quad_perm:[2,3,0,1] row_mask:0xf bank_mask:0xf bound_ctrl:1
	v_pk_mul_f32 v[72:73], v[72:73], v[4:5]
	v_pk_fma_f32 v[72:73], v[6:7], v[74:75], v[72:73]
	ds_read_b128 v[56:59], v10 offset:32768
	ds_read_b128 v[60:63], v10 offset:33024
	ds_read_b128 v[48:51], v10 offset:32256
	ds_read_b128 v[64:67], v10 offset:33280
	ds_read_b128 v[52:55], v10 offset:32512
	ds_write2st64_b32 v12, v8, v9 offset0:40 offset1:42
	v_add_f32_dpp v116, v116, v116 row_half_mirror row_mask:0xf bank_mask:0xf bound_ctrl:1
	v_add_f32_e32 v8, v72, v73
	s_waitcnt lgkmcnt(6)
	v_add_f32_dpp v116, v116, v116 row_mirror row_mask:0xf bank_mask:0xf bound_ctrl:1
	v_pk_fma_f32 v[4:5], v[116:117], v[120:121], v[112:113] op_sel_hi:[0,1,1]
	v_pk_fma_f32 v[6:7], v[116:117], v[122:123], v[114:115] op_sel_hi:[0,1,1]
	v_pk_mul_f32 v[40:41], v[4:5], v[40:41]
	v_pk_fma_f32 v[40:41], v[6:7], v[42:43], v[40:41]
	v_add_f32_e32 v40, v40, v41
	v_pk_mul_f32 v[36:37], v[36:37], v[0:1] op_sel_hi:[1,0]
	v_pk_mul_f32 v[38:39], v[38:39], v[0:1] op_sel_hi:[1,0]
	v_add_f32_dpp v40, v40, v40 quad_perm:[1,0,3,2] row_mask:0xf bank_mask:0xf bound_ctrl:1
	v_pk_fma_f32 v[36:37], v[4:5], v[28:29], v[36:37]
	v_pk_fma_f32 v[38:39], v[6:7], v[30:31], v[38:39]
	v_add_f32_dpp v40, v40, v40 quad_perm:[2,3,0,1] row_mask:0xf bank_mask:0xf bound_ctrl:1
	v_pk_mul_f32 v[108:109], v[108:109], v[4:5]
	v_pk_fma_f32 v[108:109], v[6:7], v[110:111], v[108:109]
	ds_read_b128 v[76:79], v10 offset:34304
	ds_read2st64_b32 v[2:3], v11 offset0:137 offset1:143
	ds_read_b128 v[80:83], v10 offset:34560
	ds_read_b128 v[68:71], v10 offset:33792
	ds_read_b128 v[84:87], v10 offset:34816
	ds_read_b128 v[72:75], v10 offset:34048
	v_add_f32_dpp v40, v40, v40 row_half_mirror row_mask:0xf bank_mask:0xf bound_ctrl:1
	v_add_f32_e32 v9, v108, v109
	s_waitcnt lgkmcnt(7)
	v_add_f32_dpp v40, v40, v40 row_mirror row_mask:0xf bank_mask:0xf bound_ctrl:1
	v_pk_fma_f32 v[4:5], v[40:41], v[44:45], v[36:37] op_sel_hi:[0,1,1]
	v_pk_fma_f32 v[6:7], v[40:41], v[46:47], v[38:39] op_sel_hi:[0,1,1]
	v_pk_mul_f32 v[60:61], v[4:5], v[60:61]
	v_pk_fma_f32 v[60:61], v[6:7], v[62:63], v[60:61]
	v_add_f32_e32 v60, v60, v61
	v_pk_mul_f32 v[56:57], v[56:57], v[0:1] op_sel:[0,1] op_sel_hi:[1,1]
	v_pk_mul_f32 v[58:59], v[58:59], v[0:1] op_sel:[0,1] op_sel_hi:[1,1]
	v_add_f32_dpp v60, v60, v60 quad_perm:[1,0,3,2] row_mask:0xf bank_mask:0xf bound_ctrl:1
	v_pk_fma_f32 v[56:57], v[4:5], v[48:49], v[56:57]
	v_pk_fma_f32 v[58:59], v[6:7], v[50:51], v[58:59]
	v_add_f32_dpp v60, v60, v60 quad_perm:[2,3,0,1] row_mask:0xf bank_mask:0xf bound_ctrl:1
	v_pk_mul_f32 v[32:33], v[32:33], v[4:5]
	v_pk_fma_f32 v[32:33], v[6:7], v[34:35], v[32:33]
	ds_read_b128 v[112:115], v10 offset:35840
	ds_read_b128 v[116:119], v10 offset:36096
	ds_read_b128 v[104:107], v10 offset:35328
	ds_read_b128 v[120:123], v10 offset:36352
	ds_read_b128 v[108:111], v10 offset:35584
	ds_write2st64_b32 v12, v8, v9 offset0:44 offset1:46
	v_add_f32_dpp v60, v60, v60 row_half_mirror row_mask:0xf bank_mask:0xf bound_ctrl:1
	v_add_f32_e32 v8, v32, v33
	s_waitcnt lgkmcnt(6)
	v_add_f32_dpp v60, v60, v60 row_mirror row_mask:0xf bank_mask:0xf bound_ctrl:1
	v_pk_fma_f32 v[4:5], v[60:61], v[64:65], v[56:57] op_sel_hi:[0,1,1]
	v_pk_fma_f32 v[6:7], v[60:61], v[66:67], v[58:59] op_sel_hi:[0,1,1]
	v_pk_mul_f32 v[80:81], v[4:5], v[80:81]
	v_pk_fma_f32 v[80:81], v[6:7], v[82:83], v[80:81]
	v_add_f32_e32 v80, v80, v81
	v_pk_mul_f32 v[76:77], v[76:77], v[2:3] op_sel_hi:[1,0]
	v_pk_mul_f32 v[78:79], v[78:79], v[2:3] op_sel_hi:[1,0]
	v_add_f32_dpp v80, v80, v80 quad_perm:[1,0,3,2] row_mask:0xf bank_mask:0xf bound_ctrl:1
	v_pk_fma_f32 v[76:77], v[4:5], v[68:69], v[76:77]
	v_pk_fma_f32 v[78:79], v[6:7], v[70:71], v[78:79]
	v_add_f32_dpp v80, v80, v80 quad_perm:[2,3,0,1] row_mask:0xf bank_mask:0xf bound_ctrl:1
	v_pk_mul_f32 v[52:53], v[52:53], v[4:5]
	v_pk_fma_f32 v[52:53], v[6:7], v[54:55], v[52:53]
	ds_read_b128 v[36:39], v10 offset:37376
	ds_read2st64_b32 v[0:1], v11 offset0:149 offset1:155
	ds_read_b128 v[40:43], v10 offset:37632
	ds_read_b128 v[28:31], v10 offset:36864
	ds_read_b128 v[44:47], v10 offset:37888
	ds_read_b128 v[32:35], v10 offset:37120
	v_add_f32_dpp v80, v80, v80 row_half_mirror row_mask:0xf bank_mask:0xf bound_ctrl:1
	v_add_f32_e32 v9, v52, v53
	s_waitcnt lgkmcnt(7)
	v_add_f32_dpp v80, v80, v80 row_mirror row_mask:0xf bank_mask:0xf bound_ctrl:1
	v_pk_fma_f32 v[4:5], v[80:81], v[84:85], v[76:77] op_sel_hi:[0,1,1]
	v_pk_fma_f32 v[6:7], v[80:81], v[86:87], v[78:79] op_sel_hi:[0,1,1]
	v_pk_mul_f32 v[116:117], v[4:5], v[116:117]
	v_pk_fma_f32 v[116:117], v[6:7], v[118:119], v[116:117]
	v_add_f32_e32 v116, v116, v117
	v_pk_mul_f32 v[112:113], v[112:113], v[2:3] op_sel:[0,1] op_sel_hi:[1,1]
	v_pk_mul_f32 v[114:115], v[114:115], v[2:3] op_sel:[0,1] op_sel_hi:[1,1]
	v_add_f32_dpp v116, v116, v116 quad_perm:[1,0,3,2] row_mask:0xf bank_mask:0xf bound_ctrl:1
	v_pk_fma_f32 v[112:113], v[4:5], v[104:105], v[112:113]
	v_pk_fma_f32 v[114:115], v[6:7], v[106:107], v[114:115]
	v_add_f32_dpp v116, v116, v116 quad_perm:[2,3,0,1] row_mask:0xf bank_mask:0xf bound_ctrl:1
	v_pk_mul_f32 v[72:73], v[72:73], v[4:5]
	v_pk_fma_f32 v[72:73], v[6:7], v[74:75], v[72:73]
	ds_read_b128 v[56:59], v10 offset:38912
	ds_read_b128 v[60:63], v10 offset:39168
	ds_read_b128 v[48:51], v10 offset:38400
	ds_read_b128 v[64:67], v10 offset:39424
	ds_read_b128 v[52:55], v10 offset:38656
	ds_write2st64_b32 v12, v8, v9 offset0:48 offset1:50
	v_add_f32_dpp v116, v116, v116 row_half_mirror row_mask:0xf bank_mask:0xf bound_ctrl:1
	v_add_f32_e32 v8, v72, v73
	s_waitcnt lgkmcnt(6)
	v_add_f32_dpp v116, v116, v116 row_mirror row_mask:0xf bank_mask:0xf bound_ctrl:1
	v_pk_fma_f32 v[4:5], v[116:117], v[120:121], v[112:113] op_sel_hi:[0,1,1]
	v_pk_fma_f32 v[6:7], v[116:117], v[122:123], v[114:115] op_sel_hi:[0,1,1]
	v_pk_mul_f32 v[40:41], v[4:5], v[40:41]
	v_pk_fma_f32 v[40:41], v[6:7], v[42:43], v[40:41]
	v_add_f32_e32 v40, v40, v41
	v_pk_mul_f32 v[36:37], v[36:37], v[0:1] op_sel_hi:[1,0]
	v_pk_mul_f32 v[38:39], v[38:39], v[0:1] op_sel_hi:[1,0]
	v_add_f32_dpp v40, v40, v40 quad_perm:[1,0,3,2] row_mask:0xf bank_mask:0xf bound_ctrl:1
	v_pk_fma_f32 v[36:37], v[4:5], v[28:29], v[36:37]
	v_pk_fma_f32 v[38:39], v[6:7], v[30:31], v[38:39]
	v_add_f32_dpp v40, v40, v40 quad_perm:[2,3,0,1] row_mask:0xf bank_mask:0xf bound_ctrl:1
	v_pk_mul_f32 v[108:109], v[108:109], v[4:5]
	v_pk_fma_f32 v[108:109], v[6:7], v[110:111], v[108:109]
	ds_read_b128 v[76:79], v10 offset:40448
	ds_read2st64_b32 v[2:3], v11 offset0:161 offset1:167
	ds_read_b128 v[80:83], v10 offset:40704
	ds_read_b128 v[68:71], v10 offset:39936
	ds_read_b128 v[84:87], v10 offset:40960
	ds_read_b128 v[72:75], v10 offset:40192
	v_add_f32_dpp v40, v40, v40 row_half_mirror row_mask:0xf bank_mask:0xf bound_ctrl:1
	v_add_f32_e32 v9, v108, v109
	s_waitcnt lgkmcnt(7)
	v_add_f32_dpp v40, v40, v40 row_mirror row_mask:0xf bank_mask:0xf bound_ctrl:1
	v_pk_fma_f32 v[4:5], v[40:41], v[44:45], v[36:37] op_sel_hi:[0,1,1]
	v_pk_fma_f32 v[6:7], v[40:41], v[46:47], v[38:39] op_sel_hi:[0,1,1]
	v_pk_mul_f32 v[60:61], v[4:5], v[60:61]
	v_pk_fma_f32 v[60:61], v[6:7], v[62:63], v[60:61]
	v_add_f32_e32 v60, v60, v61
	v_pk_mul_f32 v[56:57], v[56:57], v[0:1] op_sel:[0,1] op_sel_hi:[1,1]
	v_pk_mul_f32 v[58:59], v[58:59], v[0:1] op_sel:[0,1] op_sel_hi:[1,1]
	v_add_f32_dpp v60, v60, v60 quad_perm:[1,0,3,2] row_mask:0xf bank_mask:0xf bound_ctrl:1
	v_pk_fma_f32 v[56:57], v[4:5], v[48:49], v[56:57]
	v_pk_fma_f32 v[58:59], v[6:7], v[50:51], v[58:59]
	v_add_f32_dpp v60, v60, v60 quad_perm:[2,3,0,1] row_mask:0xf bank_mask:0xf bound_ctrl:1
	v_pk_mul_f32 v[32:33], v[32:33], v[4:5]
	v_pk_fma_f32 v[32:33], v[6:7], v[34:35], v[32:33]
	ds_read_b128 v[112:115], v10 offset:41984
	ds_read_b128 v[116:119], v10 offset:42240
	ds_read_b128 v[104:107], v10 offset:41472
	ds_read_b128 v[120:123], v10 offset:42496
	ds_read_b128 v[108:111], v10 offset:41728
	ds_write2st64_b32 v12, v8, v9 offset0:52 offset1:54
	v_add_f32_dpp v60, v60, v60 row_half_mirror row_mask:0xf bank_mask:0xf bound_ctrl:1
	v_add_f32_e32 v8, v32, v33
	s_waitcnt lgkmcnt(6)
	v_add_f32_dpp v60, v60, v60 row_mirror row_mask:0xf bank_mask:0xf bound_ctrl:1
	v_pk_fma_f32 v[4:5], v[60:61], v[64:65], v[56:57] op_sel_hi:[0,1,1]
	v_pk_fma_f32 v[6:7], v[60:61], v[66:67], v[58:59] op_sel_hi:[0,1,1]
	v_pk_mul_f32 v[80:81], v[4:5], v[80:81]
	v_pk_fma_f32 v[80:81], v[6:7], v[82:83], v[80:81]
	v_add_f32_e32 v80, v80, v81
	v_pk_mul_f32 v[76:77], v[76:77], v[2:3] op_sel_hi:[1,0]
	v_pk_mul_f32 v[78:79], v[78:79], v[2:3] op_sel_hi:[1,0]
	v_add_f32_dpp v80, v80, v80 quad_perm:[1,0,3,2] row_mask:0xf bank_mask:0xf bound_ctrl:1
	v_pk_fma_f32 v[76:77], v[4:5], v[68:69], v[76:77]
	v_pk_fma_f32 v[78:79], v[6:7], v[70:71], v[78:79]
	v_add_f32_dpp v80, v80, v80 quad_perm:[2,3,0,1] row_mask:0xf bank_mask:0xf bound_ctrl:1
	v_pk_mul_f32 v[52:53], v[52:53], v[4:5]
	v_pk_fma_f32 v[52:53], v[6:7], v[54:55], v[52:53]
	ds_read_b128 v[36:39], v10 offset:43520
	ds_read2st64_b32 v[0:1], v11 offset0:173 offset1:179
	ds_read_b128 v[40:43], v10 offset:43776
	ds_read_b128 v[28:31], v10 offset:43008
	ds_read_b128 v[44:47], v10 offset:44032
	ds_read_b128 v[32:35], v10 offset:43264
	v_add_f32_dpp v80, v80, v80 row_half_mirror row_mask:0xf bank_mask:0xf bound_ctrl:1
	v_add_f32_e32 v9, v52, v53
	s_waitcnt lgkmcnt(7)
	v_add_f32_dpp v80, v80, v80 row_mirror row_mask:0xf bank_mask:0xf bound_ctrl:1
	v_pk_fma_f32 v[4:5], v[80:81], v[84:85], v[76:77] op_sel_hi:[0,1,1]
	v_pk_fma_f32 v[6:7], v[80:81], v[86:87], v[78:79] op_sel_hi:[0,1,1]
	v_pk_mul_f32 v[116:117], v[4:5], v[116:117]
	v_pk_fma_f32 v[116:117], v[6:7], v[118:119], v[116:117]
	v_add_f32_e32 v116, v116, v117
	v_pk_mul_f32 v[112:113], v[112:113], v[2:3] op_sel:[0,1] op_sel_hi:[1,1]
	v_pk_mul_f32 v[114:115], v[114:115], v[2:3] op_sel:[0,1] op_sel_hi:[1,1]
	v_add_f32_dpp v116, v116, v116 quad_perm:[1,0,3,2] row_mask:0xf bank_mask:0xf bound_ctrl:1
	v_pk_fma_f32 v[112:113], v[4:5], v[104:105], v[112:113]
	v_pk_fma_f32 v[114:115], v[6:7], v[106:107], v[114:115]
	v_add_f32_dpp v116, v116, v116 quad_perm:[2,3,0,1] row_mask:0xf bank_mask:0xf bound_ctrl:1
	v_pk_mul_f32 v[72:73], v[72:73], v[4:5]
	v_pk_fma_f32 v[72:73], v[6:7], v[74:75], v[72:73]
	ds_read_b128 v[56:59], v10 offset:45056
	ds_read_b128 v[60:63], v10 offset:45312
	ds_read_b128 v[48:51], v10 offset:44544
	ds_read_b128 v[64:67], v10 offset:45568
	ds_read_b128 v[52:55], v10 offset:44800
	ds_write2st64_b32 v12, v8, v9 offset0:56 offset1:58
	v_add_f32_dpp v116, v116, v116 row_half_mirror row_mask:0xf bank_mask:0xf bound_ctrl:1
	v_add_f32_e32 v8, v72, v73
	s_waitcnt lgkmcnt(6)
	v_add_f32_dpp v116, v116, v116 row_mirror row_mask:0xf bank_mask:0xf bound_ctrl:1
	v_pk_fma_f32 v[4:5], v[116:117], v[120:121], v[112:113] op_sel_hi:[0,1,1]
	v_pk_fma_f32 v[6:7], v[116:117], v[122:123], v[114:115] op_sel_hi:[0,1,1]
	v_pk_mul_f32 v[40:41], v[4:5], v[40:41]
	v_pk_fma_f32 v[40:41], v[6:7], v[42:43], v[40:41]
	v_add_f32_e32 v40, v40, v41
	v_pk_mul_f32 v[36:37], v[36:37], v[0:1] op_sel_hi:[1,0]
	v_pk_mul_f32 v[38:39], v[38:39], v[0:1] op_sel_hi:[1,0]
	v_add_f32_dpp v40, v40, v40 quad_perm:[1,0,3,2] row_mask:0xf bank_mask:0xf bound_ctrl:1
	v_pk_fma_f32 v[36:37], v[4:5], v[28:29], v[36:37]
	v_pk_fma_f32 v[38:39], v[6:7], v[30:31], v[38:39]
	v_add_f32_dpp v40, v40, v40 quad_perm:[2,3,0,1] row_mask:0xf bank_mask:0xf bound_ctrl:1
	v_pk_mul_f32 v[108:109], v[108:109], v[4:5]
	v_pk_fma_f32 v[108:109], v[6:7], v[110:111], v[108:109]
	ds_read_b128 v[76:79], v10 offset:46592
	ds_read2st64_b32 v[2:3], v11 offset0:185 offset1:191
	ds_read_b128 v[80:83], v10 offset:46848
	ds_read_b128 v[68:71], v10 offset:46080
	ds_read_b128 v[84:87], v10 offset:47104
	ds_read_b128 v[72:75], v10 offset:46336
	v_add_f32_dpp v40, v40, v40 row_half_mirror row_mask:0xf bank_mask:0xf bound_ctrl:1
	v_add_f32_e32 v9, v108, v109
	s_waitcnt lgkmcnt(7)
	v_add_f32_dpp v40, v40, v40 row_mirror row_mask:0xf bank_mask:0xf bound_ctrl:1
	v_pk_fma_f32 v[4:5], v[40:41], v[44:45], v[36:37] op_sel_hi:[0,1,1]
	v_pk_fma_f32 v[6:7], v[40:41], v[46:47], v[38:39] op_sel_hi:[0,1,1]
	v_pk_mul_f32 v[60:61], v[4:5], v[60:61]
	v_pk_fma_f32 v[60:61], v[6:7], v[62:63], v[60:61]
	v_add_f32_e32 v60, v60, v61
	v_pk_mul_f32 v[56:57], v[56:57], v[0:1] op_sel:[0,1] op_sel_hi:[1,1]
	v_pk_mul_f32 v[58:59], v[58:59], v[0:1] op_sel:[0,1] op_sel_hi:[1,1]
	v_add_f32_dpp v60, v60, v60 quad_perm:[1,0,3,2] row_mask:0xf bank_mask:0xf bound_ctrl:1
	v_pk_fma_f32 v[56:57], v[4:5], v[48:49], v[56:57]
	v_pk_fma_f32 v[58:59], v[6:7], v[50:51], v[58:59]
	v_add_f32_dpp v60, v60, v60 quad_perm:[2,3,0,1] row_mask:0xf bank_mask:0xf bound_ctrl:1
	v_pk_mul_f32 v[32:33], v[32:33], v[4:5]
	v_pk_fma_f32 v[32:33], v[6:7], v[34:35], v[32:33]
	ds_read_b128 v[112:115], v10 offset:48128
	ds_read_b128 v[116:119], v10 offset:48384
	ds_read_b128 v[104:107], v10 offset:47616
	ds_read_b128 v[120:123], v10 offset:48640
	ds_read_b128 v[108:111], v10 offset:47872
	ds_write2st64_b32 v12, v8, v9 offset0:60 offset1:62
	v_add_f32_dpp v60, v60, v60 row_half_mirror row_mask:0xf bank_mask:0xf bound_ctrl:1
	v_add_f32_e32 v8, v32, v33
	s_waitcnt lgkmcnt(6)
	v_add_f32_dpp v60, v60, v60 row_mirror row_mask:0xf bank_mask:0xf bound_ctrl:1
